# K-loop: dedicated last trip for a workgroup's last unit (no harmless re-read DMAs, waits recounted 8/2/0) on top of the hand-written weight conversion version
# speedup vs baseline: 1.0032x; 1.0032x over previous
; #define PG8_STAGE(bufoff, gbase, voff) do { _Pragma("unroll") for (int _i = 0; _i < 2; ++_i) \
;         __builtin_amdgcn_global_load_lds((const unsigned*)((const char*)(gbase) + (voff)[_i]), (PG8_LAS unsigned*)(lds + (bufoff) + ldsw + _i * 8192), 16, 0, 0); } while (0)
; #define PG8_LDA(dst, b, h) do { _Pragma("unroll") for (int m = 0; m < 4; ++m) _Pragma("unroll") for (int k = 0; k < 2; ++k) dst[m][k] = *(const PG8_LAS bf16x8*)(lds + PG8_SA(b, h) + aoff + m * 2048 + k * 1024); } while (0)
; #define PG8_LDB(dst, b, h) do { _Pragma("unroll") for (int n = 0; n < 2; ++n) _Pragma("unroll") for (int k = 0; k < 2; ++k) dst[n][k] = *(const PG8_LAS bf16x8*)(lds + PG8_SB(b, h) + boff + n * 2048 + k * 1024); } while (0)
; #define PG8_MMA(ai, bj, At, Bt) do { __builtin_amdgcn_s_setprio(1); _Pragma("unroll") for (int m = 0; m < 4; ++m) _Pragma("unroll") for (int n = 0; n < 2; ++n) _Pragma("unroll") for (int k = 0; k < 2; ++k) \
;         acc[ai][bj][m][n] = __builtin_amdgcn_mfma_f32_16x16x32_bf16(Bt[n][k], At[m][k], acc[ai][bj][m][n], 0, 0, 0); __builtin_amdgcn_s_setprio(0); } while (0)
; #define PG8_WAIT_V(n) asm volatile("s_waitcnt vmcnt(" #n ")" ::: "memory")
; #define PG8_WAIT_L(n) asm volatile("s_waitcnt lgkmcnt(" #n ")" ::: "memory")
; template <class Epi, class Sched, bool ALIGN_EPI = false, bool SP2 = false>
; __device__ __forceinline__ void gemm_phase(PG8_LAS unsigned char* lds, const Gemm g, const Sched& S, const Epi& E) {
;     ...
;             const bool last = (t == nt - 2);
;             const char* a1 = cA + (size_t)(t + 1) * kstep;
;             const char* a2 = last ? nA : cA + (size_t)(t + 2) * kstep; const char* b2 = last ? nB : cB + (size_t)(t + 2) * kstep;
;             const char* a3 = a2 + kstep; const char* b3 = b2 + kstep;
;             if (last && has_next) S.a_ready(nxt);
;             if constexpr (SP2) {
;             PG8_LDB(B0, 0, 0); PG8_LDB(B1, 0, 1); PG8_SCHED; PG8_LDA(At, 0, 0); PG8_STAGE(PG8_SA(1, 1), a1 + hstep, voffA);
;             PG8_WAIT_V(8); PG8_WAIT_L(0); PG8_BAR; PG8_MMA(0, 0, At, B0); PG8_MMA(0, 1, At, B1); PG8_BAR; PG8_SCHED;
;             PG8_LDA(At, 0, 1); PG8_STAGE(PG8_SB(0, 0), b2, voffB); PG8_STAGE(PG8_SB(0, 1), b2 + hstep, voffB); PG8_STAGE(PG8_SA(0, 0), a2, voffA);
;             PG8_WAIT_V(8); PG8_WAIT_L(0); PG8_BAR; PG8_MMA(1, 0, At, B0); PG8_MMA(1, 1, At, B1); PG8_BAR; PG8_SCHED;
.LBB0_300:
	s_cmp_eq_u32 s96, s8
	s_cbranch_scc0 .Lk_body
	s_cmp_lg_u64 s[4:5], 0
	s_cbranch_scc1 .Lk_final
.Lk_body:
	s_add_i32 s82, s8, 2
	s_add_u32 s46, s6, 0x80
	s_addc_u32 s9, s7, 0
	s_cmp_eq_u32 s96, s8
	s_cselect_b32 s9, s79, s9
	s_cselect_b32 s8, s78, s46
	s_cselect_b32 s47, s81, vcc_hi
	s_cselect_b32 s46, s80, vcc_lo
	ds_read_b128 v[142:145], v232
	ds_read_b128 v[146:149], v232 offset:1024
	ds_read_b128 v[174:177], v232 offset:2048
	ds_read_b128 v[178:181], v232 offset:3072
	ds_read_b128 v[182:185], v232 offset:16384
	ds_read_b128 v[186:189], v232 offset:17408
	ds_read_b128 v[190:193], v232 offset:18432
	ds_read_b128 v[194:197], v232 offset:19456
	s_add_i32 m0, s68, 0xc000
	ds_read_b128 v[198:201], v173
	ds_read_b128 v[202:205], v173 offset:1024
	ds_read_b128 v[206:209], v173 offset:2048
	ds_read_b128 v[210:213], v173 offset:3072
	ds_read_b128 v[214:217], v173 offset:4096
	ds_read_b128 v[218:221], v173 offset:5120
	ds_read_b128 v[222:225], v173 offset:6144
	ds_read_b128 v[226:229], v173 offset:7168
	global_load_lds_dwordx4 v140, s[6:7]
	s_add_i32 m0, s68, 0xe000
	s_nop 0
	global_load_lds_dwordx4 v138, s[6:7]
	s_waitcnt vmcnt(8)
	s_waitcnt lgkmcnt(0)
	s_barrier
	s_setprio 1
	v_mfma_f32_16x16x32_bf16 v[124:127], v[142:145], v[198:201], v[124:127]
	v_mfma_f32_16x16x32_bf16 v[120:123], v[174:177], v[198:201], v[120:123]
	v_mfma_f32_16x16x32_bf16 v[108:111], v[142:145], v[206:209], v[108:111]
	v_mfma_f32_16x16x32_bf16 v[104:107], v[174:177], v[206:209], v[104:107]
	v_mfma_f32_16x16x32_bf16 v[92:95], v[142:145], v[214:217], v[92:95]
	v_mfma_f32_16x16x32_bf16 v[88:91], v[174:177], v[214:217], v[88:91]
	v_mfma_f32_16x16x32_bf16 v[76:79], v[142:145], v[222:225], v[76:79]
	v_mfma_f32_16x16x32_bf16 v[72:75], v[174:177], v[222:225], v[72:75]
	v_mfma_f32_16x16x32_bf16 v[124:127], v[146:149], v[202:205], v[124:127]
	v_mfma_f32_16x16x32_bf16 v[120:123], v[178:181], v[202:205], v[120:123]
	v_mfma_f32_16x16x32_bf16 v[108:111], v[146:149], v[210:213], v[108:111]
	v_mfma_f32_16x16x32_bf16 v[104:107], v[178:181], v[210:213], v[104:107]
	v_mfma_f32_16x16x32_bf16 v[92:95], v[146:149], v[218:221], v[92:95]
	v_mfma_f32_16x16x32_bf16 v[88:91], v[178:181], v[218:221], v[88:91]
	v_mfma_f32_16x16x32_bf16 v[76:79], v[146:149], v[226:229], v[76:79]
	v_mfma_f32_16x16x32_bf16 v[72:75], v[178:181], v[226:229], v[72:75]
	s_setprio 0
	s_setprio 1
	v_mfma_f32_16x16x32_bf16 v[116:119], v[182:185], v[198:201], v[116:119]
	v_mfma_f32_16x16x32_bf16 v[112:115], v[190:193], v[198:201], v[112:115]
	v_mfma_f32_16x16x32_bf16 v[100:103], v[182:185], v[206:209], v[100:103]
	v_mfma_f32_16x16x32_bf16 v[96:99], v[190:193], v[206:209], v[96:99]
	v_mfma_f32_16x16x32_bf16 v[84:87], v[182:185], v[214:217], v[84:87]
	v_mfma_f32_16x16x32_bf16 v[80:83], v[190:193], v[214:217], v[80:83]
	v_mfma_f32_16x16x32_bf16 v[68:71], v[182:185], v[222:225], v[68:71]
	v_mfma_f32_16x16x32_bf16 v[64:67], v[190:193], v[222:225], v[64:67]
	v_mfma_f32_16x16x32_bf16 v[116:119], v[186:189], v[202:205], v[116:119]
	v_mfma_f32_16x16x32_bf16 v[112:115], v[194:197], v[202:205], v[112:115]
	v_mfma_f32_16x16x32_bf16 v[100:103], v[186:189], v[210:213], v[100:103]
	v_mfma_f32_16x16x32_bf16 v[96:99], v[194:197], v[210:213], v[96:99]
	v_mfma_f32_16x16x32_bf16 v[84:87], v[186:189], v[218:221], v[84:87]
	v_mfma_f32_16x16x32_bf16 v[80:83], v[194:197], v[218:221], v[80:83]
	v_mfma_f32_16x16x32_bf16 v[68:71], v[186:189], v[226:229], v[68:71]
	v_mfma_f32_16x16x32_bf16 v[64:67], v[194:197], v[226:229], v[64:67]
	s_setprio 0
	s_barrier
	s_add_i32 m0, s65, 0x10000
	ds_read_b128 v[198:201], v173 offset:16384
	ds_read_b128 v[202:205], v173 offset:17408
	ds_read_b128 v[206:209], v173 offset:18432
	ds_read_b128 v[210:213], v173 offset:19456
	ds_read_b128 v[214:217], v173 offset:20480
	ds_read_b128 v[218:221], v173 offset:21504
	ds_read_b128 v[222:225], v173 offset:22528
	ds_read_b128 v[226:229], v173 offset:23552
	global_load_lds_dwordx4 v128, s[46:47]
	s_add_i32 m0, s65, 0x12000
	s_nop 0
	global_load_lds_dwordx4 v136, s[46:47]
	s_add_i32 m0, s65, 0x14000
	s_nop 0
	global_load_lds_dwordx4 v230, s[46:47]
	s_add_i32 m0, s65, 0x16000
	s_nop 0
	global_load_lds_dwordx4 v231, s[46:47]
	s_mov_b32 m0, s68
	s_nop 0
	global_load_lds_dwordx4 v132, s[8:9]
	s_mov_b32 m0, s87
	s_nop 0
	global_load_lds_dwordx4 v134, s[8:9]
	s_waitcnt vmcnt(8)
	s_waitcnt lgkmcnt(0)
	s_barrier
	s_setprio 1
	v_mfma_f32_16x16x32_bf16 v[60:63], v[142:145], v[198:201], v[60:63]
	v_mfma_f32_16x16x32_bf16 v[56:59], v[174:177], v[198:201], v[56:59]
	v_mfma_f32_16x16x32_bf16 v[44:47], v[142:145], v[206:209], v[44:47]
	v_mfma_f32_16x16x32_bf16 v[40:43], v[174:177], v[206:209], v[40:43]
	v_mfma_f32_16x16x32_bf16 v[28:31], v[142:145], v[214:217], v[28:31]
	v_mfma_f32_16x16x32_bf16 v[24:27], v[174:177], v[214:217], v[24:27]
	v_mfma_f32_16x16x32_bf16 v[12:15], v[142:145], v[222:225], v[12:15]
	v_mfma_f32_16x16x32_bf16 v[8:11], v[174:177], v[222:225], v[8:11]
	v_mfma_f32_16x16x32_bf16 v[60:63], v[146:149], v[202:205], v[60:63]
	v_mfma_f32_16x16x32_bf16 v[56:59], v[178:181], v[202:205], v[56:59]
	v_mfma_f32_16x16x32_bf16 v[44:47], v[146:149], v[210:213], v[44:47]
	v_mfma_f32_16x16x32_bf16 v[40:43], v[178:181], v[210:213], v[40:43]
	v_mfma_f32_16x16x32_bf16 v[28:31], v[146:149], v[218:221], v[28:31]
	v_mfma_f32_16x16x32_bf16 v[24:27], v[178:181], v[218:221], v[24:27]
	v_mfma_f32_16x16x32_bf16 v[12:15], v[146:149], v[226:229], v[12:15]
	v_mfma_f32_16x16x32_bf16 v[8:11], v[178:181], v[226:229], v[8:11]
	s_setprio 0
	s_setprio 1
	v_mfma_f32_16x16x32_bf16 v[52:55], v[182:185], v[198:201], v[52:55]
	v_mfma_f32_16x16x32_bf16 v[48:51], v[190:193], v[198:201], v[48:51]
	v_mfma_f32_16x16x32_bf16 v[36:39], v[182:185], v[206:209], v[36:39]
	v_mfma_f32_16x16x32_bf16 v[32:35], v[190:193], v[206:209], v[32:35]
	v_mfma_f32_16x16x32_bf16 v[20:23], v[182:185], v[214:217], v[20:23]
	v_mfma_f32_16x16x32_bf16 v[16:19], v[190:193], v[214:217], v[16:19]
	v_mfma_f32_16x16x32_bf16 v[4:7], v[182:185], v[222:225], v[4:7]
	v_mfma_f32_16x16x32_bf16 v[0:3], v[190:193], v[222:225], v[0:3]
	v_mfma_f32_16x16x32_bf16 v[52:55], v[186:189], v[202:205], v[52:55]
	v_mfma_f32_16x16x32_bf16 v[48:51], v[194:197], v[202:205], v[48:51]
	v_mfma_f32_16x16x32_bf16 v[36:39], v[186:189], v[210:213], v[36:39]
	v_mfma_f32_16x16x32_bf16 v[32:35], v[194:197], v[210:213], v[32:35]
	v_mfma_f32_16x16x32_bf16 v[20:23], v[186:189], v[218:221], v[20:23]
	v_mfma_f32_16x16x32_bf16 v[16:19], v[194:197], v[218:221], v[16:19]
	v_mfma_f32_16x16x32_bf16 v[4:7], v[186:189], v[226:229], v[4:7]
	v_mfma_f32_16x16x32_bf16 v[0:3], v[194:197], v[226:229], v[0:3]
	s_setprio 0
	s_barrier
; #define PG8_STAGE(bufoff, gbase, voff) do { _Pragma("unroll") for (int _i = 0; _i < 2; ++_i) \
;         __builtin_amdgcn_global_load_lds((const unsigned*)((const char*)(gbase) + (voff)[_i]), (PG8_LAS unsigned*)(lds + (bufoff) + ldsw + _i * 8192), 16, 0, 0); } while (0)
; #define PG8_LDA(dst, b, h) do { _Pragma("unroll") for (int m = 0; m < 4; ++m) _Pragma("unroll") for (int k = 0; k < 2; ++k) dst[m][k] = *(const PG8_LAS bf16x8*)(lds + PG8_SA(b, h) + aoff + m * 2048 + k * 1024); } while (0)
; #define PG8_LDB(dst, b, h) do { _Pragma("unroll") for (int n = 0; n < 2; ++n) _Pragma("unroll") for (int k = 0; k < 2; ++k) dst[n][k] = *(const PG8_LAS bf16x8*)(lds + PG8_SB(b, h) + boff + n * 2048 + k * 1024); } while (0)
; #define PG8_MMA(ai, bj, At, Bt) do { __builtin_amdgcn_s_setprio(1); _Pragma("unroll") for (int m = 0; m < 4; ++m) _Pragma("unroll") for (int n = 0; n < 2; ++n) _Pragma("unroll") for (int k = 0; k < 2; ++k) \
;         acc[ai][bj][m][n] = __builtin_amdgcn_mfma_f32_16x16x32_bf16(Bt[n][k], At[m][k], acc[ai][bj][m][n], 0, 0, 0); __builtin_amdgcn_s_setprio(0); } while (0)
; #define PG8_WAIT_V(n) asm volatile("s_waitcnt vmcnt(" #n ")" ::: "memory")
; #define PG8_WAIT_L(n) asm volatile("s_waitcnt lgkmcnt(" #n ")" ::: "memory")
; #define PG8_BAR __builtin_amdgcn_s_barrier()
; #define PG8_SCHED __builtin_amdgcn_sched_barrier(0)
; template <class Epi, class Sched, bool ALIGN_EPI = false, bool SP2 = false>
; __device__ __forceinline__ void gemm_phase(PG8_LAS unsigned char* lds, const Gemm g, const Sched& S, const Epi& E) {
;     ...
;             PG8_LDB(B0, 1, 0); PG8_LDB(B1, 1, 1); PG8_SCHED; PG8_LDA(At, 1, 0); PG8_STAGE(PG8_SA(0, 1), a2 + hstep, voffA);
;             PG8_WAIT_V(8); PG8_WAIT_L(0); PG8_BAR; PG8_MMA(0, 0, At, B0); PG8_MMA(0, 1, At, B1); PG8_BAR; PG8_SCHED;
;             PG8_LDA(At, 1, 1); PG8_STAGE(PG8_SB(1, 0), b3, voffB); PG8_STAGE(PG8_SB(1, 1), b3 + hstep, voffB); PG8_STAGE(PG8_SA(1, 0), a3, voffA);
;             PG8_WAIT_V(8); PG8_WAIT_L(0); PG8_BAR; PG8_MMA(1, 0, At, B0); PG8_MMA(1, 1, At, B1); PG8_BAR; PG8_SCHED;
	ds_read_b128 v[142:145], v232 offset:32768
	ds_read_b128 v[146:149], v232 offset:33792
	ds_read_b128 v[174:177], v232 offset:34816
	ds_read_b128 v[178:181], v232 offset:35840
	ds_read_b128 v[182:185], v232 offset:49152
	ds_read_b128 v[186:189], v232 offset:50176
	ds_read_b128 v[190:193], v232 offset:51200
	ds_read_b128 v[194:197], v232 offset:52224
	s_mov_b32 m0, s1
	ds_read_b128 v[198:201], v173 offset:32768
	ds_read_b128 v[202:205], v173 offset:33792
	ds_read_b128 v[206:209], v173 offset:34816
	ds_read_b128 v[210:213], v173 offset:35840
	ds_read_b128 v[214:217], v173 offset:36864
	ds_read_b128 v[218:221], v173 offset:37888
	ds_read_b128 v[222:225], v173 offset:38912
	ds_read_b128 v[226:229], v173 offset:39936
	global_load_lds_dwordx4 v140, s[8:9]
	s_mov_b32 m0, s0
	s_nop 0
	global_load_lds_dwordx4 v138, s[8:9]
	s_waitcnt vmcnt(8)
	s_waitcnt lgkmcnt(0)
	s_barrier
	s_setprio 1
	v_mfma_f32_16x16x32_bf16 v[124:127], v[142:145], v[198:201], v[124:127]
	v_mfma_f32_16x16x32_bf16 v[120:123], v[174:177], v[198:201], v[120:123]
	v_mfma_f32_16x16x32_bf16 v[108:111], v[142:145], v[206:209], v[108:111]
	v_mfma_f32_16x16x32_bf16 v[104:107], v[174:177], v[206:209], v[104:107]
	v_mfma_f32_16x16x32_bf16 v[92:95], v[142:145], v[214:217], v[92:95]
	v_mfma_f32_16x16x32_bf16 v[88:91], v[174:177], v[214:217], v[88:91]
	v_mfma_f32_16x16x32_bf16 v[76:79], v[142:145], v[222:225], v[76:79]
	v_mfma_f32_16x16x32_bf16 v[72:75], v[174:177], v[222:225], v[72:75]
	v_mfma_f32_16x16x32_bf16 v[124:127], v[146:149], v[202:205], v[124:127]
	v_mfma_f32_16x16x32_bf16 v[120:123], v[178:181], v[202:205], v[120:123]
	v_mfma_f32_16x16x32_bf16 v[108:111], v[146:149], v[210:213], v[108:111]
	v_mfma_f32_16x16x32_bf16 v[104:107], v[178:181], v[210:213], v[104:107]
	v_mfma_f32_16x16x32_bf16 v[92:95], v[146:149], v[218:221], v[92:95]
	v_mfma_f32_16x16x32_bf16 v[88:91], v[178:181], v[218:221], v[88:91]
	v_mfma_f32_16x16x32_bf16 v[76:79], v[146:149], v[226:229], v[76:79]
	v_mfma_f32_16x16x32_bf16 v[72:75], v[178:181], v[226:229], v[72:75]
	s_setprio 0
	s_setprio 1
	v_mfma_f32_16x16x32_bf16 v[116:119], v[182:185], v[198:201], v[116:119]
	v_mfma_f32_16x16x32_bf16 v[112:115], v[190:193], v[198:201], v[112:115]
	v_mfma_f32_16x16x32_bf16 v[100:103], v[182:185], v[206:209], v[100:103]
	v_mfma_f32_16x16x32_bf16 v[96:99], v[190:193], v[206:209], v[96:99]
	v_mfma_f32_16x16x32_bf16 v[84:87], v[182:185], v[214:217], v[84:87]
	v_mfma_f32_16x16x32_bf16 v[80:83], v[190:193], v[214:217], v[80:83]
	v_mfma_f32_16x16x32_bf16 v[68:71], v[182:185], v[222:225], v[68:71]
	v_mfma_f32_16x16x32_bf16 v[64:67], v[190:193], v[222:225], v[64:67]
	v_mfma_f32_16x16x32_bf16 v[116:119], v[186:189], v[202:205], v[116:119]
	v_mfma_f32_16x16x32_bf16 v[112:115], v[194:197], v[202:205], v[112:115]
	v_mfma_f32_16x16x32_bf16 v[100:103], v[186:189], v[210:213], v[100:103]
	v_mfma_f32_16x16x32_bf16 v[96:99], v[194:197], v[210:213], v[96:99]
	v_mfma_f32_16x16x32_bf16 v[84:87], v[186:189], v[218:221], v[84:87]
	v_mfma_f32_16x16x32_bf16 v[80:83], v[194:197], v[218:221], v[80:83]
	v_mfma_f32_16x16x32_bf16 v[68:71], v[186:189], v[226:229], v[68:71]
	v_mfma_f32_16x16x32_bf16 v[64:67], v[194:197], v[226:229], v[64:67]
	s_setprio 0
	s_barrier
	s_add_i32 m0, s65, 0x17f80
	ds_read_b128 v[198:201], v173 offset:49152
	ds_read_b128 v[202:205], v173 offset:50176
	ds_read_b128 v[206:209], v173 offset:51200
	ds_read_b128 v[210:213], v173 offset:52224
	ds_read_b128 v[214:217], v173 offset:53248
	ds_read_b128 v[218:221], v173 offset:54272
	ds_read_b128 v[222:225], v173 offset:55296
	ds_read_b128 v[226:229], v173 offset:56320
	global_load_lds_dwordx4 v128, s[46:47] offset:128
	s_add_i32 m0, s65, 0x19f80
	s_nop 0
	global_load_lds_dwordx4 v136, s[46:47] offset:128
	s_add_i32 m0, s65, 0x1bf80
	s_nop 0
	global_load_lds_dwordx4 v230, s[46:47] offset:128
	s_add_i32 m0, s65, 0x1df80
	s_nop 0
	global_load_lds_dwordx4 v231, s[46:47] offset:128
	s_add_i32 m0, s88, 0xffffff80
	s_nop 0
	global_load_lds_dwordx4 v132, s[8:9] offset:128
	s_add_i32 m0, s95, 0xffffff80
	s_nop 0
	global_load_lds_dwordx4 v134, s[8:9] offset:128
	s_waitcnt vmcnt(8)
	s_waitcnt lgkmcnt(0)
	s_barrier
	s_setprio 1
	v_mfma_f32_16x16x32_bf16 v[60:63], v[142:145], v[198:201], v[60:63]
	v_mfma_f32_16x16x32_bf16 v[56:59], v[174:177], v[198:201], v[56:59]
	v_mfma_f32_16x16x32_bf16 v[44:47], v[142:145], v[206:209], v[44:47]
	v_mfma_f32_16x16x32_bf16 v[40:43], v[174:177], v[206:209], v[40:43]
	v_mfma_f32_16x16x32_bf16 v[28:31], v[142:145], v[214:217], v[28:31]
	v_mfma_f32_16x16x32_bf16 v[24:27], v[174:177], v[214:217], v[24:27]
	v_mfma_f32_16x16x32_bf16 v[12:15], v[142:145], v[222:225], v[12:15]
	v_mfma_f32_16x16x32_bf16 v[8:11], v[174:177], v[222:225], v[8:11]
	v_mfma_f32_16x16x32_bf16 v[60:63], v[146:149], v[202:205], v[60:63]
	v_mfma_f32_16x16x32_bf16 v[56:59], v[178:181], v[202:205], v[56:59]
	v_mfma_f32_16x16x32_bf16 v[44:47], v[146:149], v[210:213], v[44:47]
	v_mfma_f32_16x16x32_bf16 v[40:43], v[178:181], v[210:213], v[40:43]
	v_mfma_f32_16x16x32_bf16 v[28:31], v[146:149], v[218:221], v[28:31]
	v_mfma_f32_16x16x32_bf16 v[24:27], v[178:181], v[218:221], v[24:27]
	v_mfma_f32_16x16x32_bf16 v[12:15], v[146:149], v[226:229], v[12:15]
	v_mfma_f32_16x16x32_bf16 v[8:11], v[178:181], v[226:229], v[8:11]
	s_setprio 0
	s_setprio 1
	v_mfma_f32_16x16x32_bf16 v[52:55], v[182:185], v[198:201], v[52:55]
	v_mfma_f32_16x16x32_bf16 v[48:51], v[190:193], v[198:201], v[48:51]
	v_mfma_f32_16x16x32_bf16 v[36:39], v[182:185], v[206:209], v[36:39]
	v_mfma_f32_16x16x32_bf16 v[32:35], v[190:193], v[206:209], v[32:35]
	v_mfma_f32_16x16x32_bf16 v[20:23], v[182:185], v[214:217], v[20:23]
	v_mfma_f32_16x16x32_bf16 v[16:19], v[190:193], v[214:217], v[16:19]
	v_mfma_f32_16x16x32_bf16 v[4:7], v[182:185], v[222:225], v[4:7]
	v_mfma_f32_16x16x32_bf16 v[0:3], v[190:193], v[222:225], v[0:3]
	v_mfma_f32_16x16x32_bf16 v[52:55], v[186:189], v[202:205], v[52:55]
	v_mfma_f32_16x16x32_bf16 v[48:51], v[194:197], v[202:205], v[48:51]
	v_mfma_f32_16x16x32_bf16 v[36:39], v[186:189], v[210:213], v[36:39]
	v_mfma_f32_16x16x32_bf16 v[32:35], v[194:197], v[210:213], v[32:35]
	v_mfma_f32_16x16x32_bf16 v[20:23], v[186:189], v[218:221], v[20:23]
	v_mfma_f32_16x16x32_bf16 v[16:19], v[194:197], v[218:221], v[16:19]
	v_mfma_f32_16x16x32_bf16 v[4:7], v[186:189], v[226:229], v[4:7]
	v_mfma_f32_16x16x32_bf16 v[0:3], v[194:197], v[226:229], v[0:3]
	s_setprio 0
	s_barrier
	s_add_u32 vcc_lo, vcc_lo, 0x100
	s_addc_u32 vcc_hi, vcc_hi, 0
	s_add_u32 s6, s6, 0x100
	s_addc_u32 s7, s7, 0
	s_cmp_ge_u32 s82, s97
	s_mov_b32 s8, s82
	s_cbranch_scc0 .LBB0_300
	s_branch .Lk_done
; #define PG8_STAGE(bufoff, gbase, voff) do { _Pragma("unroll") for (int _i = 0; _i < 2; ++_i) \
;         __builtin_amdgcn_global_load_lds((const unsigned*)((const char*)(gbase) + (voff)[_i]), (PG8_LAS unsigned*)(lds + (bufoff) + ldsw + _i * 8192), 16, 0, 0); } while (0)
; #define PG8_LDA(dst, b, h) do { _Pragma("unroll") for (int m = 0; m < 4; ++m) _Pragma("unroll") for (int k = 0; k < 2; ++k) dst[m][k] = *(const PG8_LAS bf16x8*)(lds + PG8_SA(b, h) + aoff + m * 2048 + k * 1024); } while (0)
; #define PG8_LDB(dst, b, h) do { _Pragma("unroll") for (int n = 0; n < 2; ++n) _Pragma("unroll") for (int k = 0; k < 2; ++k) dst[n][k] = *(const PG8_LAS bf16x8*)(lds + PG8_SB(b, h) + boff + n * 2048 + k * 1024); } while (0)
; #define PG8_MMA(ai, bj, At, Bt) do { __builtin_amdgcn_s_setprio(1); _Pragma("unroll") for (int m = 0; m < 4; ++m) _Pragma("unroll") for (int n = 0; n < 2; ++n) _Pragma("unroll") for (int k = 0; k < 2; ++k) \
;         acc[ai][bj][m][n] = __builtin_amdgcn_mfma_f32_16x16x32_bf16(Bt[n][k], At[m][k], acc[ai][bj][m][n], 0, 0, 0); __builtin_amdgcn_s_setprio(0); } while (0)
; #define PG8_WAIT_V(n) asm volatile("s_waitcnt vmcnt(" #n ")" ::: "memory")
; #define PG8_WAIT_L(n) asm volatile("s_waitcnt lgkmcnt(" #n ")" ::: "memory")
; #define PG8_BAR __builtin_amdgcn_s_barrier()
; #define PG8_SCHED __builtin_amdgcn_sched_barrier(0)
; template <class Epi, class Sched, bool ALIGN_EPI = false, bool SP2 = false>
; __device__ __forceinline__ void gemm_phase(PG8_LAS unsigned char* lds, const Gemm g, const Sched& S, const Epi& E) {
;     ...
;             PG8_LDB(B0, 0, 0); PG8_LDB(B1, 0, 1); PG8_SCHED; PG8_LDA(At, 0, 0); PG8_STAGE(PG8_SA(1, 1), a1 + hstep, voffA);
;             PG8_WAIT_V(8); PG8_WAIT_L(0); PG8_BAR; PG8_MMA(0, 0, At, B0); PG8_MMA(0, 1, At, B1); PG8_BAR; PG8_SCHED;
;             PG8_LDA(At, 0, 1); PG8_STAGE(PG8_SB(0, 0), b2, voffB); PG8_STAGE(PG8_SB(0, 1), b2 + hstep, voffB); PG8_STAGE(PG8_SA(0, 0), a2, voffA);
;             PG8_WAIT_V(8); PG8_WAIT_L(0); PG8_BAR; PG8_MMA(1, 0, At, B0); PG8_MMA(1, 1, At, B1); PG8_BAR; PG8_SCHED;
.Lk_final:
	s_add_i32 s82, s8, 2
	s_add_u32 s46, s6, 0x80
	s_addc_u32 s9, s7, 0
	s_cmp_eq_u32 s96, s8
	s_cselect_b32 s9, s79, s9
	s_cselect_b32 s8, s78, s46
	s_cselect_b32 s47, s81, vcc_hi
	s_cselect_b32 s46, s80, vcc_lo
	ds_read_b128 v[142:145], v232
	ds_read_b128 v[146:149], v232 offset:1024
	ds_read_b128 v[174:177], v232 offset:2048
	ds_read_b128 v[178:181], v232 offset:3072
	ds_read_b128 v[182:185], v232 offset:16384
	ds_read_b128 v[186:189], v232 offset:17408
	ds_read_b128 v[190:193], v232 offset:18432
	ds_read_b128 v[194:197], v232 offset:19456
	s_add_i32 m0, s68, 0xc000
	ds_read_b128 v[198:201], v173
	ds_read_b128 v[202:205], v173 offset:1024
	ds_read_b128 v[206:209], v173 offset:2048
	ds_read_b128 v[210:213], v173 offset:3072
	ds_read_b128 v[214:217], v173 offset:4096
	ds_read_b128 v[218:221], v173 offset:5120
	ds_read_b128 v[222:225], v173 offset:6144
	ds_read_b128 v[226:229], v173 offset:7168
	global_load_lds_dwordx4 v140, s[6:7]
	s_add_i32 m0, s68, 0xe000
	s_nop 0
	global_load_lds_dwordx4 v138, s[6:7]
	s_waitcnt vmcnt(8)
	s_waitcnt lgkmcnt(0)
	s_barrier
	s_setprio 1
	v_mfma_f32_16x16x32_bf16 v[124:127], v[142:145], v[198:201], v[124:127]
	v_mfma_f32_16x16x32_bf16 v[120:123], v[174:177], v[198:201], v[120:123]
	v_mfma_f32_16x16x32_bf16 v[108:111], v[142:145], v[206:209], v[108:111]
	v_mfma_f32_16x16x32_bf16 v[104:107], v[174:177], v[206:209], v[104:107]
	v_mfma_f32_16x16x32_bf16 v[92:95], v[142:145], v[214:217], v[92:95]
	v_mfma_f32_16x16x32_bf16 v[88:91], v[174:177], v[214:217], v[88:91]
	v_mfma_f32_16x16x32_bf16 v[76:79], v[142:145], v[222:225], v[76:79]
	v_mfma_f32_16x16x32_bf16 v[72:75], v[174:177], v[222:225], v[72:75]
	v_mfma_f32_16x16x32_bf16 v[124:127], v[146:149], v[202:205], v[124:127]
	v_mfma_f32_16x16x32_bf16 v[120:123], v[178:181], v[202:205], v[120:123]
	v_mfma_f32_16x16x32_bf16 v[108:111], v[146:149], v[210:213], v[108:111]
	v_mfma_f32_16x16x32_bf16 v[104:107], v[178:181], v[210:213], v[104:107]
	v_mfma_f32_16x16x32_bf16 v[92:95], v[146:149], v[218:221], v[92:95]
	v_mfma_f32_16x16x32_bf16 v[88:91], v[178:181], v[218:221], v[88:91]
	v_mfma_f32_16x16x32_bf16 v[76:79], v[146:149], v[226:229], v[76:79]
	v_mfma_f32_16x16x32_bf16 v[72:75], v[178:181], v[226:229], v[72:75]
	s_setprio 0
	s_setprio 1
	v_mfma_f32_16x16x32_bf16 v[116:119], v[182:185], v[198:201], v[116:119]
	v_mfma_f32_16x16x32_bf16 v[112:115], v[190:193], v[198:201], v[112:115]
	v_mfma_f32_16x16x32_bf16 v[100:103], v[182:185], v[206:209], v[100:103]
	v_mfma_f32_16x16x32_bf16 v[96:99], v[190:193], v[206:209], v[96:99]
	v_mfma_f32_16x16x32_bf16 v[84:87], v[182:185], v[214:217], v[84:87]
	v_mfma_f32_16x16x32_bf16 v[80:83], v[190:193], v[214:217], v[80:83]
	v_mfma_f32_16x16x32_bf16 v[68:71], v[182:185], v[222:225], v[68:71]
	v_mfma_f32_16x16x32_bf16 v[64:67], v[190:193], v[222:225], v[64:67]
	v_mfma_f32_16x16x32_bf16 v[116:119], v[186:189], v[202:205], v[116:119]
	v_mfma_f32_16x16x32_bf16 v[112:115], v[194:197], v[202:205], v[112:115]
	v_mfma_f32_16x16x32_bf16 v[100:103], v[186:189], v[210:213], v[100:103]
	v_mfma_f32_16x16x32_bf16 v[96:99], v[194:197], v[210:213], v[96:99]
	v_mfma_f32_16x16x32_bf16 v[84:87], v[186:189], v[218:221], v[84:87]
	v_mfma_f32_16x16x32_bf16 v[80:83], v[194:197], v[218:221], v[80:83]
	v_mfma_f32_16x16x32_bf16 v[68:71], v[186:189], v[226:229], v[68:71]
	v_mfma_f32_16x16x32_bf16 v[64:67], v[194:197], v[226:229], v[64:67]
	s_setprio 0
	s_barrier
	ds_read_b128 v[198:201], v173 offset:16384
	ds_read_b128 v[202:205], v173 offset:17408
	ds_read_b128 v[206:209], v173 offset:18432
	ds_read_b128 v[210:213], v173 offset:19456
	ds_read_b128 v[214:217], v173 offset:20480
	ds_read_b128 v[218:221], v173 offset:21504
	ds_read_b128 v[222:225], v173 offset:22528
	ds_read_b128 v[226:229], v173 offset:23552
	s_waitcnt vmcnt(2)
	s_waitcnt lgkmcnt(0)
	s_barrier
	s_setprio 1
	v_mfma_f32_16x16x32_bf16 v[60:63], v[142:145], v[198:201], v[60:63]
	v_mfma_f32_16x16x32_bf16 v[56:59], v[174:177], v[198:201], v[56:59]
	v_mfma_f32_16x16x32_bf16 v[44:47], v[142:145], v[206:209], v[44:47]
	v_mfma_f32_16x16x32_bf16 v[40:43], v[174:177], v[206:209], v[40:43]
	v_mfma_f32_16x16x32_bf16 v[28:31], v[142:145], v[214:217], v[28:31]
	v_mfma_f32_16x16x32_bf16 v[24:27], v[174:177], v[214:217], v[24:27]
	v_mfma_f32_16x16x32_bf16 v[12:15], v[142:145], v[222:225], v[12:15]
	v_mfma_f32_16x16x32_bf16 v[8:11], v[174:177], v[222:225], v[8:11]
	v_mfma_f32_16x16x32_bf16 v[60:63], v[146:149], v[202:205], v[60:63]
	v_mfma_f32_16x16x32_bf16 v[56:59], v[178:181], v[202:205], v[56:59]
	v_mfma_f32_16x16x32_bf16 v[44:47], v[146:149], v[210:213], v[44:47]
	v_mfma_f32_16x16x32_bf16 v[40:43], v[178:181], v[210:213], v[40:43]
	v_mfma_f32_16x16x32_bf16 v[28:31], v[146:149], v[218:221], v[28:31]
	v_mfma_f32_16x16x32_bf16 v[24:27], v[178:181], v[218:221], v[24:27]
	v_mfma_f32_16x16x32_bf16 v[12:15], v[146:149], v[226:229], v[12:15]
	v_mfma_f32_16x16x32_bf16 v[8:11], v[178:181], v[226:229], v[8:11]
	s_setprio 0
	s_setprio 1
	v_mfma_f32_16x16x32_bf16 v[52:55], v[182:185], v[198:201], v[52:55]
	v_mfma_f32_16x16x32_bf16 v[48:51], v[190:193], v[198:201], v[48:51]
	v_mfma_f32_16x16x32_bf16 v[36:39], v[182:185], v[206:209], v[36:39]
	v_mfma_f32_16x16x32_bf16 v[32:35], v[190:193], v[206:209], v[32:35]
	v_mfma_f32_16x16x32_bf16 v[20:23], v[182:185], v[214:217], v[20:23]
	v_mfma_f32_16x16x32_bf16 v[16:19], v[190:193], v[214:217], v[16:19]
	v_mfma_f32_16x16x32_bf16 v[4:7], v[182:185], v[222:225], v[4:7]
	v_mfma_f32_16x16x32_bf16 v[0:3], v[190:193], v[222:225], v[0:3]
	v_mfma_f32_16x16x32_bf16 v[52:55], v[186:189], v[202:205], v[52:55]
	v_mfma_f32_16x16x32_bf16 v[48:51], v[194:197], v[202:205], v[48:51]
	v_mfma_f32_16x16x32_bf16 v[36:39], v[186:189], v[210:213], v[36:39]
	v_mfma_f32_16x16x32_bf16 v[32:35], v[194:197], v[210:213], v[32:35]
	v_mfma_f32_16x16x32_bf16 v[20:23], v[186:189], v[218:221], v[20:23]
	v_mfma_f32_16x16x32_bf16 v[16:19], v[194:197], v[218:221], v[16:19]
	v_mfma_f32_16x16x32_bf16 v[4:7], v[186:189], v[226:229], v[4:7]
	v_mfma_f32_16x16x32_bf16 v[0:3], v[194:197], v[226:229], v[0:3]
	s_setprio 0
	s_barrier
; #define PG8_STAGE(bufoff, gbase, voff) do { _Pragma("unroll") for (int _i = 0; _i < 2; ++_i) \
;         __builtin_amdgcn_global_load_lds((const unsigned*)((const char*)(gbase) + (voff)[_i]), (PG8_LAS unsigned*)(lds + (bufoff) + ldsw + _i * 8192), 16, 0, 0); } while (0)
; #define PG8_LDA(dst, b, h) do { _Pragma("unroll") for (int m = 0; m < 4; ++m) _Pragma("unroll") for (int k = 0; k < 2; ++k) dst[m][k] = *(const PG8_LAS bf16x8*)(lds + PG8_SA(b, h) + aoff + m * 2048 + k * 1024); } while (0)
; #define PG8_LDB(dst, b, h) do { _Pragma("unroll") for (int n = 0; n < 2; ++n) _Pragma("unroll") for (int k = 0; k < 2; ++k) dst[n][k] = *(const PG8_LAS bf16x8*)(lds + PG8_SB(b, h) + boff + n * 2048 + k * 1024); } while (0)
; #define PG8_MMA(ai, bj, At, Bt) do { __builtin_amdgcn_s_setprio(1); _Pragma("unroll") for (int m = 0; m < 4; ++m) _Pragma("unroll") for (int n = 0; n < 2; ++n) _Pragma("unroll") for (int k = 0; k < 2; ++k) \
;         acc[ai][bj][m][n] = __builtin_amdgcn_mfma_f32_16x16x32_bf16(Bt[n][k], At[m][k], acc[ai][bj][m][n], 0, 0, 0); __builtin_amdgcn_s_setprio(0); } while (0)
; #define PG8_WAIT_V(n) asm volatile("s_waitcnt vmcnt(" #n ")" ::: "memory")
; #define PG8_WAIT_L(n) asm volatile("s_waitcnt lgkmcnt(" #n ")" ::: "memory")
; #define PG8_BAR __builtin_amdgcn_s_barrier()
; #define PG8_SCHED __builtin_amdgcn_sched_barrier(0)
; template <class Epi, class Sched, bool ALIGN_EPI = false, bool SP2 = false>
; __device__ __forceinline__ void gemm_phase(PG8_LAS unsigned char* lds, const Gemm g, const Sched& S, const Epi& E) {
;     ...
;             PG8_LDB(B0, 1, 0); PG8_LDB(B1, 1, 1); PG8_SCHED; PG8_LDA(At, 1, 0); PG8_STAGE(PG8_SA(0, 1), a2 + hstep, voffA);
;             PG8_WAIT_V(8); PG8_WAIT_L(0); PG8_BAR; PG8_MMA(0, 0, At, B0); PG8_MMA(0, 1, At, B1); PG8_BAR; PG8_SCHED;
;             PG8_LDA(At, 1, 1); PG8_STAGE(PG8_SB(1, 0), b3, voffB); PG8_STAGE(PG8_SB(1, 1), b3 + hstep, voffB); PG8_STAGE(PG8_SA(1, 0), a3, voffA);
;             PG8_WAIT_V(8); PG8_WAIT_L(0); PG8_BAR; PG8_MMA(1, 0, At, B0); PG8_MMA(1, 1, At, B1); PG8_BAR; PG8_SCHED;
	ds_read_b128 v[142:145], v232 offset:32768
	ds_read_b128 v[146:149], v232 offset:33792
	ds_read_b128 v[174:177], v232 offset:34816
	ds_read_b128 v[178:181], v232 offset:35840
	ds_read_b128 v[182:185], v232 offset:49152
	ds_read_b128 v[186:189], v232 offset:50176
	ds_read_b128 v[190:193], v232 offset:51200
	ds_read_b128 v[194:197], v232 offset:52224
	ds_read_b128 v[198:201], v173 offset:32768
	ds_read_b128 v[202:205], v173 offset:33792
	ds_read_b128 v[206:209], v173 offset:34816
	ds_read_b128 v[210:213], v173 offset:35840
	ds_read_b128 v[214:217], v173 offset:36864
	ds_read_b128 v[218:221], v173 offset:37888
	ds_read_b128 v[222:225], v173 offset:38912
	ds_read_b128 v[226:229], v173 offset:39936
	s_waitcnt vmcnt(0)
	s_waitcnt lgkmcnt(0)
	s_barrier
	s_setprio 1
	v_mfma_f32_16x16x32_bf16 v[124:127], v[142:145], v[198:201], v[124:127]
	v_mfma_f32_16x16x32_bf16 v[120:123], v[174:177], v[198:201], v[120:123]
	v_mfma_f32_16x16x32_bf16 v[108:111], v[142:145], v[206:209], v[108:111]
	v_mfma_f32_16x16x32_bf16 v[104:107], v[174:177], v[206:209], v[104:107]
	v_mfma_f32_16x16x32_bf16 v[92:95], v[142:145], v[214:217], v[92:95]
	v_mfma_f32_16x16x32_bf16 v[88:91], v[174:177], v[214:217], v[88:91]
	v_mfma_f32_16x16x32_bf16 v[76:79], v[142:145], v[222:225], v[76:79]
	v_mfma_f32_16x16x32_bf16 v[72:75], v[174:177], v[222:225], v[72:75]
	v_mfma_f32_16x16x32_bf16 v[124:127], v[146:149], v[202:205], v[124:127]
	v_mfma_f32_16x16x32_bf16 v[120:123], v[178:181], v[202:205], v[120:123]
	v_mfma_f32_16x16x32_bf16 v[108:111], v[146:149], v[210:213], v[108:111]
	v_mfma_f32_16x16x32_bf16 v[104:107], v[178:181], v[210:213], v[104:107]
	v_mfma_f32_16x16x32_bf16 v[92:95], v[146:149], v[218:221], v[92:95]
	v_mfma_f32_16x16x32_bf16 v[88:91], v[178:181], v[218:221], v[88:91]
	v_mfma_f32_16x16x32_bf16 v[76:79], v[146:149], v[226:229], v[76:79]
	v_mfma_f32_16x16x32_bf16 v[72:75], v[178:181], v[226:229], v[72:75]
	s_setprio 0
	s_setprio 1
	v_mfma_f32_16x16x32_bf16 v[116:119], v[182:185], v[198:201], v[116:119]
	v_mfma_f32_16x16x32_bf16 v[112:115], v[190:193], v[198:201], v[112:115]
	v_mfma_f32_16x16x32_bf16 v[100:103], v[182:185], v[206:209], v[100:103]
	v_mfma_f32_16x16x32_bf16 v[96:99], v[190:193], v[206:209], v[96:99]
	v_mfma_f32_16x16x32_bf16 v[84:87], v[182:185], v[214:217], v[84:87]
	v_mfma_f32_16x16x32_bf16 v[80:83], v[190:193], v[214:217], v[80:83]
	v_mfma_f32_16x16x32_bf16 v[68:71], v[182:185], v[222:225], v[68:71]
	v_mfma_f32_16x16x32_bf16 v[64:67], v[190:193], v[222:225], v[64:67]
	v_mfma_f32_16x16x32_bf16 v[116:119], v[186:189], v[202:205], v[116:119]
	v_mfma_f32_16x16x32_bf16 v[112:115], v[194:197], v[202:205], v[112:115]
	v_mfma_f32_16x16x32_bf16 v[100:103], v[186:189], v[210:213], v[100:103]
	v_mfma_f32_16x16x32_bf16 v[96:99], v[194:197], v[210:213], v[96:99]
	v_mfma_f32_16x16x32_bf16 v[84:87], v[186:189], v[218:221], v[84:87]
	v_mfma_f32_16x16x32_bf16 v[80:83], v[194:197], v[218:221], v[80:83]
	v_mfma_f32_16x16x32_bf16 v[68:71], v[186:189], v[226:229], v[68:71]
	v_mfma_f32_16x16x32_bf16 v[64:67], v[194:197], v[226:229], v[64:67]
	s_setprio 0
	s_barrier
	ds_read_b128 v[198:201], v173 offset:49152
	ds_read_b128 v[202:205], v173 offset:50176
	ds_read_b128 v[206:209], v173 offset:51200
	ds_read_b128 v[210:213], v173 offset:52224
	ds_read_b128 v[214:217], v173 offset:53248
	ds_read_b128 v[218:221], v173 offset:54272
	ds_read_b128 v[222:225], v173 offset:55296
	ds_read_b128 v[226:229], v173 offset:56320
	s_waitcnt lgkmcnt(0)
	s_barrier
	s_setprio 1
	v_mfma_f32_16x16x32_bf16 v[60:63], v[142:145], v[198:201], v[60:63]
	v_mfma_f32_16x16x32_bf16 v[56:59], v[174:177], v[198:201], v[56:59]
	v_mfma_f32_16x16x32_bf16 v[44:47], v[142:145], v[206:209], v[44:47]
	v_mfma_f32_16x16x32_bf16 v[40:43], v[174:177], v[206:209], v[40:43]
	v_mfma_f32_16x16x32_bf16 v[28:31], v[142:145], v[214:217], v[28:31]
	v_mfma_f32_16x16x32_bf16 v[24:27], v[174:177], v[214:217], v[24:27]
	v_mfma_f32_16x16x32_bf16 v[12:15], v[142:145], v[222:225], v[12:15]
	v_mfma_f32_16x16x32_bf16 v[8:11], v[174:177], v[222:225], v[8:11]
	v_mfma_f32_16x16x32_bf16 v[60:63], v[146:149], v[202:205], v[60:63]
	v_mfma_f32_16x16x32_bf16 v[56:59], v[178:181], v[202:205], v[56:59]
	v_mfma_f32_16x16x32_bf16 v[44:47], v[146:149], v[210:213], v[44:47]
	v_mfma_f32_16x16x32_bf16 v[40:43], v[178:181], v[210:213], v[40:43]
	v_mfma_f32_16x16x32_bf16 v[28:31], v[146:149], v[218:221], v[28:31]
	v_mfma_f32_16x16x32_bf16 v[24:27], v[178:181], v[218:221], v[24:27]
	v_mfma_f32_16x16x32_bf16 v[12:15], v[146:149], v[226:229], v[12:15]
	v_mfma_f32_16x16x32_bf16 v[8:11], v[178:181], v[226:229], v[8:11]
	s_setprio 0
	s_setprio 1
	v_mfma_f32_16x16x32_bf16 v[52:55], v[182:185], v[198:201], v[52:55]
	v_mfma_f32_16x16x32_bf16 v[48:51], v[190:193], v[198:201], v[48:51]
	v_mfma_f32_16x16x32_bf16 v[36:39], v[182:185], v[206:209], v[36:39]
	v_mfma_f32_16x16x32_bf16 v[32:35], v[190:193], v[206:209], v[32:35]
	v_mfma_f32_16x16x32_bf16 v[20:23], v[182:185], v[214:217], v[20:23]
	v_mfma_f32_16x16x32_bf16 v[16:19], v[190:193], v[214:217], v[16:19]
	v_mfma_f32_16x16x32_bf16 v[4:7], v[182:185], v[222:225], v[4:7]
	v_mfma_f32_16x16x32_bf16 v[0:3], v[190:193], v[222:225], v[0:3]
	v_mfma_f32_16x16x32_bf16 v[52:55], v[186:189], v[202:205], v[52:55]
	v_mfma_f32_16x16x32_bf16 v[48:51], v[194:197], v[202:205], v[48:51]
	v_mfma_f32_16x16x32_bf16 v[36:39], v[186:189], v[210:213], v[36:39]
	v_mfma_f32_16x16x32_bf16 v[32:35], v[194:197], v[210:213], v[32:35]
	v_mfma_f32_16x16x32_bf16 v[20:23], v[186:189], v[218:221], v[20:23]
	v_mfma_f32_16x16x32_bf16 v[16:19], v[194:197], v[218:221], v[16:19]
	v_mfma_f32_16x16x32_bf16 v[4:7], v[186:189], v[226:229], v[4:7]
	v_mfma_f32_16x16x32_bf16 v[0:3], v[194:197], v[226:229], v[0:3]
	s_setprio 0
	s_barrier
	s_add_u32 vcc_lo, vcc_lo, 0x100
	s_addc_u32 vcc_hi, vcc_hi, 0
	s_add_u32 s6, s6, 0x100
	s_addc_u32 s7, s7, 0
